# attention PV region of half-step 2: mask temporaries renamed out of the packed-P registers so the VALU spreads evenly over the MFMA gaps
# speedup vs baseline: 1.0018x; 1.0018x over previous
; __device__ __forceinline__ void sel_mask_tile(f32x16& p0, f32x16& p1, unsigned wlo, unsigned whi, int hi) {
;     const unsigned NEGB = 0xff800000u;
;     const unsigned lo = wlo >> (4 * hi), h2 = whi >> (4 * hi);
; #pragma unroll
;     for (int r = 0; r < 16; ++r) {
;         const int c = (r & 3) + 8 * (r >> 2);
;         const unsigned m0 = (unsigned)__builtin_amdgcn_sbfe((int)lo, c, 1), m1 = (unsigned)__builtin_amdgcn_sbfe((int)h2, c, 1);
;         p0[r] = __uint_as_float((__float_as_uint(p0[r]) & m0) | (NEGB & ~m0));
;         p1[r] = __uint_as_float((__float_as_uint(p1[r]) & m1) | (NEGB & ~m1));
;     }
; }
; __device__ __forceinline__ void partialSM(f32x16& p0, f32x16& p1, float& m_reg, float& mn, float& alpha) {
;     float pmax = p0[0];
; #pragma unroll
;     for (int r = 1; r < 16; ++r) pmax = fmaxf(pmax, p0[r]);
; #pragma unroll
;     for (int r = 0; r < 16; ++r) pmax = fmaxf(pmax, p1[r]);
;     { auto rr = __builtin_amdgcn_permlane32_swap(__float_as_uint(pmax), __float_as_uint(pmax), false, false);
;       pmax = fmaxf(__uint_as_float(rr[0]), __uint_as_float(rr[1])); }
;     constexpr float C2 = 1.4426950408889634f * SCALE;
;     if (__builtin_expect(__all((pmax - m_reg) * SCALE <= THR), 1)) { mn = m_reg; alpha = 1.f; }
; template <int VB>
; __device__ __forceinline__ void pv_tile(f32x16* o, int vb0, bf16x8 pa0, bf16x8 pa1, bf16x8 pa2, bf16x8 pa3) {
;     ...
;     PV_D0(0); PV_D0(1); PV_D0(2); PV_D0(3);
.LBB0_1305:
	ds_read_b64_tr_b16 v[212:213], v1 offset:0x4000
	ds_read_b64_tr_b16 v[214:215], v1 offset:0x4800
	ds_read_b64_tr_b16 v[216:217], v1 offset:0x4200
	ds_read_b64_tr_b16 v[218:219], v1 offset:0x4a00
	ds_read_b64_tr_b16 v[220:221], v1 offset:0x4400
	ds_read_b64_tr_b16 v[222:223], v1 offset:0x4c00
	ds_read_b64_tr_b16 v[224:225], v1 offset:0x4600
	ds_read_b64_tr_b16 v[226:227], v1 offset:0x4e00
	ds_read_b64_tr_b16 v[232:233], v1 offset:0x5000
	ds_read_b64_tr_b16 v[234:235], v1 offset:0x5800
	ds_read_b64_tr_b16 v[236:237], v1 offset:0x5200
	ds_read_b64_tr_b16 v[238:239], v1 offset:0x5a00
	ds_read_b64_tr_b16 v[240:241], v1 offset:0x5400
	ds_read_b64_tr_b16 v[242:243], v1 offset:0x5c00
	s_nop 0
	s_waitcnt lgkmcnt(12)
	v_mfma_f32_32x32x16_bf16 v[2:17], v[146:149], v[212:215], v[2:17]
	ds_read_b64_tr_b16 v[244:245], v1 offset:0x5600
	ds_read_b64_tr_b16 v[246:247], v1 offset:0x5e00
	s_waitcnt vmcnt(4)
	v_lshrrev_b32_e32 v193, v163, v228
	v_bfe_i32 v192, v193, 0, 1
	v_bitop3_b32 v192, v82, s74, v192 bitop3:0xe4
	v_bfe_i32 v82, v193, 1, 1
	s_waitcnt lgkmcnt(12)
	v_mfma_f32_32x32x16_bf16 v[50:65], v[146:149], v[216:219], v[50:65]
	ds_read_b64_tr_b16 v[248:249], v1 offset:0x6000
	ds_read_b64_tr_b16 v[250:251], v1 offset:0x6800
	s_waitcnt lgkmcnt(12)
	v_mfma_f32_32x32x16_bf16 v[34:49], v[146:149], v[220:223], v[34:49]
	ds_read_b64_tr_b16 v[220:221], v1 offset:0x6200
	ds_read_b64_tr_b16 v[222:223], v1 offset:0x6a00
	s_waitcnt lgkmcnt(12)
	v_mfma_f32_32x32x16_bf16 v[18:33], v[146:149], v[224:227], v[18:33]
	ds_read_b64_tr_b16 v[224:225], v1 offset:0x6400
	ds_read_b64_tr_b16 v[226:227], v1 offset:0x6c00
	v_bitop3_b32 v146, v83, s74, v82 bitop3:0xe4
	v_bfe_i32 v82, v193, 2, 1
	v_bitop3_b32 v147, v84, s74, v82 bitop3:0xe4
	v_bfe_i32 v82, v193, 3, 1
	v_bitop3_b32 v148, v85, s74, v82 bitop3:0xe4
	v_bfe_i32 v82, v193, 8, 1
	v_bitop3_b32 v149, v86, s74, v82 bitop3:0xe4
	s_waitcnt lgkmcnt(12)
	v_mfma_f32_32x32x16_bf16 v[2:17], v[150:153], v[232:235], v[2:17]
	ds_read_b64_tr_b16 v[232:233], v1 offset:0x6600
	ds_read_b64_tr_b16 v[234:235], v1 offset:0x6e00
	v_bfe_i32 v82, v193, 9, 1
	v_bitop3_b32 v173, v87, s74, v82 bitop3:0xe4
	v_bfe_i32 v82, v193, 10, 1
	v_bitop3_b32 v88, v88, s74, v82 bitop3:0xe4
	v_bfe_i32 v82, v193, 11, 1
	v_bitop3_b32 v89, v89, s74, v82 bitop3:0xe4
	v_bfe_i32 v82, v193, 16, 1
	s_waitcnt lgkmcnt(12)
	v_mfma_f32_32x32x16_bf16 v[50:65], v[150:153], v[236:239], v[50:65]
	ds_read_b64_tr_b16 v[236:237], v1 offset:0x7000
	ds_read_b64_tr_b16 v[238:239], v1 offset:0x7800
	v_bitop3_b32 v90, v90, s74, v82 bitop3:0xe4
	v_bfe_i32 v82, v193, 17, 1
	v_bitop3_b32 v91, v91, s74, v82 bitop3:0xe4
	v_bfe_i32 v82, v193, 18, 1
	v_bitop3_b32 v92, v92, s74, v82 bitop3:0xe4
	v_bfe_i32 v82, v193, 19, 1
	v_bitop3_b32 v93, v93, s74, v82 bitop3:0xe4
	s_waitcnt lgkmcnt(12)
	v_mfma_f32_32x32x16_bf16 v[34:49], v[150:153], v[240:243], v[34:49]
	ds_read_b64_tr_b16 v[240:241], v1 offset:0x7200
	ds_read_b64_tr_b16 v[242:243], v1 offset:0x7a00
	v_bfe_i32 v82, v193, 24, 1
	v_bitop3_b32 v94, v94, s74, v82 bitop3:0xe4
	v_bfe_i32 v82, v193, 25, 1
	v_bitop3_b32 v95, v95, s74, v82 bitop3:0xe4
	v_bfe_i32 v82, v193, 26, 1
	v_bitop3_b32 v96, v96, s74, v82 bitop3:0xe4
	v_bfe_i32 v82, v193, 27, 1
	s_waitcnt lgkmcnt(12)
	v_mfma_f32_32x32x16_bf16 v[18:33], v[150:153], v[244:247], v[18:33]
	ds_read_b64_tr_b16 v[244:245], v1 offset:0x7400
	ds_read_b64_tr_b16 v[246:247], v1 offset:0x7c00
	v_bitop3_b32 v97, v97, s74, v82 bitop3:0xe4
	v_max_f32_e32 v82, v146, v146
	v_max_f32_e32 v230, v192, v192
	v_max_f32_e32 v82, v230, v82
	v_max3_f32 v82, v82, v147, v148
	v_max3_f32 v82, v82, v149, v173
	v_max3_f32 v82, v82, v88, v89
	s_waitcnt lgkmcnt(12)
	v_mfma_f32_32x32x16_bf16 v[2:17], v[154:157], v[248:251], v[2:17]
	ds_read_b64_tr_b16 v[248:249], v1 offset:0x7600
	ds_read_b64_tr_b16 v[250:251], v1 offset:0x7e00
	v_max3_f32 v82, v82, v90, v91
	v_lshrrev_b32_e32 v194, v163, v229
	v_max3_f32 v82, v82, v92, v93
	v_bfe_i32 v195, v194, 0, 1
	v_bfe_i32 v172, v194, 1, 1
	v_max3_f32 v82, v82, v94, v95
	v_bitop3_b32 v66, v66, s74, v195 bitop3:0xe4
	s_waitcnt lgkmcnt(12)
	v_mfma_f32_32x32x16_bf16 v[50:65], v[154:157], v[220:223], v[50:65]
	v_bfe_i32 v83, v194, 2, 1
	v_bfe_i32 v84, v194, 3, 1
	v_max3_f32 v230, v82, v96, v97
	v_bitop3_b32 v67, v67, s74, v172 bitop3:0xe4
	v_bfe_i32 v85, v194, 8, 1
	v_bfe_i32 v86, v194, 9, 1
	v_bitop3_b32 v82, v68, s74, v83 bitop3:0xe4
	s_waitcnt lgkmcnt(10)
	v_mfma_f32_32x32x16_bf16 v[34:49], v[154:157], v[224:227], v[34:49]
	v_max3_f32 v68, v230, v66, v67
	v_bitop3_b32 v83, v69, s74, v84 bitop3:0xe4
	v_bfe_i32 v87, v194, 10, 1
	v_bfe_i32 v230, v194, 11, 1
	v_bitop3_b32 v84, v70, s74, v85 bitop3:0xe4
	v_max3_f32 v68, v68, v82, v83
	v_bitop3_b32 v85, v71, s74, v86 bitop3:0xe4
	s_waitcnt lgkmcnt(8)
	v_mfma_f32_32x32x16_bf16 v[18:33], v[154:157], v[232:235], v[18:33]
	v_bfe_i32 v231, v194, 16, 1
	v_bfe_i32 v174, v194, 17, 1
	v_bitop3_b32 v86, v72, s74, v87 bitop3:0xe4
	v_max3_f32 v68, v68, v84, v85
	v_bitop3_b32 v87, v73, s74, v230 bitop3:0xe4
	v_bfe_i32 v230, v194, 18, 1
	v_bfe_i32 v175, v194, 19, 1
	s_waitcnt lgkmcnt(6)
	v_mfma_f32_32x32x16_bf16 v[2:17], v[158:161], v[236:239], v[2:17]
	v_bitop3_b32 v74, v74, s74, v231 bitop3:0xe4
	v_max3_f32 v69, v68, v86, v87
	v_bitop3_b32 v75, v75, s74, v174 bitop3:0xe4
	v_bfe_i32 v231, v194, 24, 1
	v_bfe_i32 v174, v194, 25, 1
	v_bitop3_b32 v68, v76, s74, v230 bitop3:0xe4
	v_max3_f32 v71, v69, v74, v75
	s_waitcnt lgkmcnt(4)
	v_mfma_f32_32x32x16_bf16 v[50:65], v[158:161], v[240:243], v[50:65]
	v_bitop3_b32 v69, v77, s74, v175 bitop3:0xe4
	v_bfe_i32 v230, v194, 26, 1
	v_bfe_i32 v175, v194, 27, 1
	v_bitop3_b32 v70, v78, s74, v231 bitop3:0xe4
	v_max3_f32 v73, v71, v68, v69
	v_bitop3_b32 v71, v79, s74, v174 bitop3:0xe4
	v_bitop3_b32 v72, v80, s74, v230 bitop3:0xe4
	s_waitcnt lgkmcnt(2)
	v_mfma_f32_32x32x16_bf16 v[34:49], v[158:161], v[244:247], v[34:49]
	v_max3_f32 v76, v73, v70, v71
	v_bitop3_b32 v73, v81, s74, v175 bitop3:0xe4
	v_max3_f32 v76, v76, v72, v73
	v_mov_b32_e32 v77, v76
	s_nop 1
	v_permlane32_swap_b32_e32 v76, v77
	v_max_f32_e32 v77, v77, v77
	s_waitcnt lgkmcnt(0)
	v_mfma_f32_32x32x16_bf16 v[18:33], v[158:161], v[248:251], v[18:33]
	s_cmp_eq_u64 s[36:37], 0
	s_cbranch_scc1 .Lp5_kw2_skip
	s_waitcnt vmcnt(0)
	ds_write_b128 v204, v[138:141] offset:49152
	ds_write_b128 v204, v[142:145] offset:57344
.Lp5_kw2_skip:
	v_max_f32_e32 v76, v76, v76
	v_max_f32_e32 v76, v76, v77
	v_sub_f32_e32 v77, v76, v206
	v_mul_f32_e32 v77, 0x3db504f3, v77
	v_cmp_ge_f32_e32 vcc, s75, v77
	s_cmp_eq_u64 vcc, exec
	s_cselect_b64 s[6:7], -1, 0
	s_andn2_b64 vcc, exec, s[36:37]
	s_barrier
	s_cbranch_vccnz .LBB0_1307
	s_waitcnt vmcnt(0)
	ds_write_b128 v197, v[130:133] offset:16384
	ds_write_b128 v198, v[134:137] offset:16384

; __device__ __forceinline__ void partialSM(f32x16& p0, f32x16& p1, float& m_reg, float& mn, float& alpha) {
;     ...
;     if (__builtin_expect(__all((pmax - m_reg) * SCALE <= THR), 1)) { mn = m_reg; alpha = 1.f; }
;     else { mn = fmaxf(m_reg, pmax); alpha = __builtin_amdgcn_exp2f((m_reg - mn) * C2); m_reg = mn; }
;     const float mnL = -mn * C2;
; #pragma unroll
;     for (int r = 0; r < 16; ++r) p0[r] = fmaf(p0[r], C2, mnL);
; #pragma unroll
;     for (int r = 0; r < 16; ++r) p1[r] = fmaf(p1[r], C2, mnL);
; #pragma unroll
;     for (int r = 0; r < 16; ++r) p0[r] = __builtin_amdgcn_exp2f(p0[r]);
; __device__ __forceinline__ void attn_block(const BlockRef& cur, const BlockRef& nxt, char* lds, Seam& S) {
;     ...
;     for (int t = 1; t + 1 < NT; t += 2) {
;         HALF_STEP(pB0, pB1, mnB, alB, pA0, pA1, alA, t, 1, 0, 0);
;         HALF_STEP(pA0, pA1, mnA, alA, pB0, pB1, alB, t + 1, 0, 1, 1);
;     }
.LBB0_1311:
	v_cndmask_b32_e64 v206, v76, v206, s[6:7]
	v_mul_f32_e32 v76, 0xbe0293ee, v206
	v_mov_b32_e32 v131, v76
	v_fmamk_f32 v77, v192, 0x3e0293ee, v76
	v_fmamk_f32 v78, v146, 0x3e0293ee, v76
	v_fmamk_f32 v79, v147, 0x3e0293ee, v76
	v_fmamk_f32 v80, v148, 0x3e0293ee, v76
	v_fmamk_f32 v81, v149, 0x3e0293ee, v76
	v_fmamk_f32 v130, v173, 0x3e0293ee, v76
	v_fmamk_f32 v88, v88, 0x3e0293ee, v76
	v_fmamk_f32 v89, v89, 0x3e0293ee, v76
	v_fmamk_f32 v90, v90, 0x3e0293ee, v76
	v_fmamk_f32 v91, v91, 0x3e0293ee, v76
	v_fmamk_f32 v92, v92, 0x3e0293ee, v76
	v_fmamk_f32 v93, v93, 0x3e0293ee, v76
	v_fmamk_f32 v94, v94, 0x3e0293ee, v76
	v_fmamk_f32 v95, v95, 0x3e0293ee, v76
	v_fmamk_f32 v96, v96, 0x3e0293ee, v76
	v_fmac_f32_e32 v131, 0x3e0293ee, v97
	v_exp_f32_e32 v219, v77
	v_exp_f32_e32 v220, v78
	v_exp_f32_e32 v221, v79
	v_exp_f32_e32 v222, v80
	v_exp_f32_e32 v223, v81
	v_exp_f32_e32 v225, v130
	v_exp_f32_e32 v224, v88
	v_exp_f32_e32 v226, v89
	v_exp_f32_e32 v211, v90
	v_exp_f32_e32 v212, v91
	v_exp_f32_e32 v213, v92
	v_exp_f32_e32 v215, v93
	v_exp_f32_e32 v214, v94
	v_exp_f32_e32 v216, v95
	v_exp_f32_e32 v217, v96
	v_exp_f32_e32 v218, v131
	v_pk_fma_f32 v[194:195], v[66:67], s[14:15], v[76:77] op_sel_hi:[1,0,0]
	v_add_f32_e32 v66, v181, v187
	v_fmac_f32_e32 v66, v177, v205
	v_add_f32_e32 v205, v209, v210
	v_pk_fma_f32 v[192:193], v[82:83], s[14:15], v[76:77] op_sel_hi:[1,0,0]
	v_pk_fma_f32 v[158:159], v[84:85], s[14:15], v[76:77] op_sel_hi:[1,0,0]
	v_pk_fma_f32 v[154:155], v[86:87], s[14:15], v[76:77] op_sel_hi:[1,0,0]
	v_pk_fma_f32 v[150:151], v[74:75], s[14:15], v[76:77] op_sel_hi:[1,0,0]
	v_pk_fma_f32 v[160:161], v[68:69], s[14:15], v[76:77] op_sel_hi:[1,0,0]
	v_pk_fma_f32 v[156:157], v[70:71], s[14:15], v[76:77] op_sel_hi:[1,0,0]
	v_pk_fma_f32 v[152:153], v[72:73], s[14:15], v[76:77] op_sel_hi:[1,0,0]
	v_fmac_f32_e32 v205, v66, v208
	v_add_u32_e32 v179, 16, v179
	v_lshl_add_u64 v[188:189], v[188:189], 0, s[16:17]
	s_cmp_ge_u32 s82, s81
	v_lshl_add_u64 v[190:191], v[190:191], 0, s[16:17]
	s_waitcnt lgkmcnt(0)
	s_barrier
	s_cbranch_scc1 .LBB0_1313
	v_mov_b32_e32 v177, v207
	s_branch .LBB0_1299
